# v17 + NSA top-k bit search: scalar s_cmp instead of VALU 64-bit compare + s_and, two tokens interleaved
# speedup vs baseline: 1.0081x; 1.0073x over previous
.LBB0_799:
	v_add_u32_e32 v1, 0, v0
	v_add_u32_e32 v4, 0x4000, v1
	ds_read2_b32 v[2:3], v1 offset1:65
	ds_read2_b32 v[4:5], v4 offset0:64 offset1:129
	ds_read2_b32 v[10:11], v1 offset0:130 offset1:195
	v_add_u32_e32 v1, 0x4200, v1
	ds_read2_b32 v[12:13], v1 offset0:66 offset1:131
	s_waitcnt lgkmcnt(2)
	v_add_f32_e32 v2, v2, v4
	v_cndmask_b32_e64 v2, v2, v233, s[0:1]
	v_cndmask_b32_e32 v7, v2, v234, vcc
	v_add_f32_e32 v3, v3, v5
	v_not_b32_e32 v2, v7
	v_or_b32_e32 v4, 0x80000000, v7
	v_cmp_gt_i32_e64 s[8:9], 0, v7
	s_nop 1
	v_cndmask_b32_e64 v8, v4, v2, s[8:9]
	v_cndmask_b32_e64 v2, v3, v233, s[0:1]
	v_cndmask_b32_e32 v5, v2, v234, vcc
	v_not_b32_e32 v1, v5
	v_or_b32_e32 v2, 0x80000000, v5
	v_cmp_gt_i32_e64 s[8:9], 0, v5
	s_nop 1
	v_cndmask_b32_e64 v6, v2, v1, s[8:9]
	s_waitcnt lgkmcnt(0)
	v_add_f32_e32 v1, v10, v12
	v_cndmask_b32_e64 v1, v1, v233, s[0:1]
	v_cndmask_b32_e32 v3, v1, v234, vcc
	v_not_b32_e32 v1, v3
	v_or_b32_e32 v2, 0x80000000, v3
	v_cmp_gt_i32_e64 s[8:9], 0, v3
	s_nop 1
	v_cndmask_b32_e64 v4, v2, v1, s[8:9]
	v_add_f32_e32 v1, v11, v13
	v_cndmask_b32_e64 v1, v1, v233, s[0:1]
	v_cndmask_b32_e32 v1, v1, v234, vcc
	v_not_b32_e32 v2, v1
	v_or_b32_e32 v9, 0x80000000, v1
	v_cmp_gt_i32_e64 s[8:9], 0, v1
	s_nop 1
	v_cndmask_b32_e64 v2, v9, v2, s[8:9]
	v_cmp_gt_i32_e64 s[8:9], 0, v8
	s_bcnt1_i32_b64 s62, s[8:9]
	v_cmp_gt_u64_e64 s[2:3], s[62:63], 15
	s_and_b64 s[2:3], s[2:3], exec
	v_cmp_gt_i32_e64 s[8:9], 0, v6
	s_cselect_b32 s12, 0x80000000, 0
	s_bcnt1_i32_b64 s62, s[8:9]
	v_cmp_gt_u64_e64 s[2:3], s[62:63], 15
	s_and_b64 s[2:3], s[2:3], exec
	v_cmp_gt_i32_e64 s[8:9], 0, v4
	s_cselect_b32 s13, 0x80000000, 0
	s_bcnt1_i32_b64 s62, s[8:9]
	v_cmp_gt_u64_e64 s[2:3], s[62:63], 15
	s_and_b64 s[2:3], s[2:3], exec
	v_cmp_gt_i32_e64 s[8:9], 0, v2
	s_cselect_b32 s14, 0x80000000, 0
	s_bcnt1_i32_b64 s62, s[8:9]
	v_cmp_gt_u64_e64 s[2:3], s[62:63], 15
	s_and_b64 s[2:3], s[2:3], exec
	s_cselect_b32 s15, 0x80000000, 0
	s_or_b32 s16, s12, 0x40000000
	s_or_b32 s95, s13, 0x40000000
	v_cmp_le_u32_e64 s[8:9], s16, v8
	v_cmp_le_u32_e64 s[2:3], s95, v6
	s_bcnt1_i32_b64 s62, s[8:9]
	s_bcnt1_i32_b64 s97, s[2:3]
	s_cmp_gt_u32 s62, 15
	s_cselect_b32 s12, s16, s12
	s_cmp_gt_u32 s97, 15
	s_cselect_b32 s13, s95, s13
	s_or_b32 s16, s14, 0x40000000
	s_or_b32 s95, s15, 0x40000000
	v_cmp_le_u32_e64 s[8:9], s16, v4
	v_cmp_le_u32_e64 s[2:3], s95, v2
	s_bcnt1_i32_b64 s62, s[8:9]
	s_bcnt1_i32_b64 s97, s[2:3]
	s_cmp_gt_u32 s62, 15
	s_cselect_b32 s14, s16, s14
	s_cmp_gt_u32 s97, 15
	s_cselect_b32 s15, s95, s15
	s_or_b32 s16, s12, 0x20000000
	s_or_b32 s95, s13, 0x20000000
	v_cmp_le_u32_e64 s[8:9], s16, v8
	v_cmp_le_u32_e64 s[2:3], s95, v6
	s_bcnt1_i32_b64 s62, s[8:9]
	s_bcnt1_i32_b64 s97, s[2:3]
	s_cmp_gt_u32 s62, 15
	s_cselect_b32 s12, s16, s12
	s_cmp_gt_u32 s97, 15
	s_cselect_b32 s13, s95, s13
	s_or_b32 s16, s14, 0x20000000
	s_or_b32 s95, s15, 0x20000000
	v_cmp_le_u32_e64 s[8:9], s16, v4
	v_cmp_le_u32_e64 s[2:3], s95, v2
	s_bcnt1_i32_b64 s62, s[8:9]
	s_bcnt1_i32_b64 s97, s[2:3]
	s_cmp_gt_u32 s62, 15
	s_cselect_b32 s14, s16, s14
	s_cmp_gt_u32 s97, 15
	s_cselect_b32 s15, s95, s15
	s_or_b32 s16, s12, 0x10000000
	s_or_b32 s95, s13, 0x10000000
	v_cmp_le_u32_e64 s[8:9], s16, v8
	v_cmp_le_u32_e64 s[2:3], s95, v6
	s_bcnt1_i32_b64 s62, s[8:9]
	s_bcnt1_i32_b64 s97, s[2:3]
	s_cmp_gt_u32 s62, 15
	s_cselect_b32 s12, s16, s12
	s_cmp_gt_u32 s97, 15
	s_cselect_b32 s13, s95, s13
	s_or_b32 s16, s14, 0x10000000
	s_or_b32 s95, s15, 0x10000000
	v_cmp_le_u32_e64 s[8:9], s16, v4
	v_cmp_le_u32_e64 s[2:3], s95, v2
	s_bcnt1_i32_b64 s62, s[8:9]
	s_bcnt1_i32_b64 s97, s[2:3]
	s_cmp_gt_u32 s62, 15
	s_cselect_b32 s14, s16, s14
	s_cmp_gt_u32 s97, 15
	s_cselect_b32 s15, s95, s15
	s_or_b32 s16, s12, 0x8000000
	s_or_b32 s95, s13, 0x8000000
	v_cmp_le_u32_e64 s[8:9], s16, v8
	v_cmp_le_u32_e64 s[2:3], s95, v6
	s_bcnt1_i32_b64 s62, s[8:9]
	s_bcnt1_i32_b64 s97, s[2:3]
	s_cmp_gt_u32 s62, 15
	s_cselect_b32 s12, s16, s12
	s_cmp_gt_u32 s97, 15
	s_cselect_b32 s13, s95, s13
	s_or_b32 s16, s14, 0x8000000
	s_or_b32 s95, s15, 0x8000000
	v_cmp_le_u32_e64 s[8:9], s16, v4
	v_cmp_le_u32_e64 s[2:3], s95, v2
	s_bcnt1_i32_b64 s62, s[8:9]
	s_bcnt1_i32_b64 s97, s[2:3]
	s_cmp_gt_u32 s62, 15
	s_cselect_b32 s14, s16, s14
	s_cmp_gt_u32 s97, 15
	s_cselect_b32 s15, s95, s15
	s_or_b32 s16, s12, 0x4000000
	s_or_b32 s95, s13, 0x4000000
	v_cmp_le_u32_e64 s[8:9], s16, v8
	v_cmp_le_u32_e64 s[2:3], s95, v6
	s_bcnt1_i32_b64 s62, s[8:9]
	s_bcnt1_i32_b64 s97, s[2:3]
	s_cmp_gt_u32 s62, 15
	s_cselect_b32 s12, s16, s12
	s_cmp_gt_u32 s97, 15
	s_cselect_b32 s13, s95, s13
	s_or_b32 s16, s14, 0x4000000
	s_or_b32 s95, s15, 0x4000000
	v_cmp_le_u32_e64 s[8:9], s16, v4
	v_cmp_le_u32_e64 s[2:3], s95, v2
	s_bcnt1_i32_b64 s62, s[8:9]
	s_bcnt1_i32_b64 s97, s[2:3]
	s_cmp_gt_u32 s62, 15
	s_cselect_b32 s14, s16, s14
	s_cmp_gt_u32 s97, 15
	s_cselect_b32 s15, s95, s15
	s_or_b32 s16, s12, 0x2000000
	s_or_b32 s95, s13, 0x2000000
	v_cmp_le_u32_e64 s[8:9], s16, v8
	v_cmp_le_u32_e64 s[2:3], s95, v6
	s_bcnt1_i32_b64 s62, s[8:9]
	s_bcnt1_i32_b64 s97, s[2:3]
	s_cmp_gt_u32 s62, 15
	s_cselect_b32 s12, s16, s12
	s_cmp_gt_u32 s97, 15
	s_cselect_b32 s13, s95, s13
	s_or_b32 s16, s14, 0x2000000
	s_or_b32 s95, s15, 0x2000000
	v_cmp_le_u32_e64 s[8:9], s16, v4
	v_cmp_le_u32_e64 s[2:3], s95, v2
	s_bcnt1_i32_b64 s62, s[8:9]
	s_bcnt1_i32_b64 s97, s[2:3]
	s_cmp_gt_u32 s62, 15
	s_cselect_b32 s14, s16, s14
	s_cmp_gt_u32 s97, 15
	s_cselect_b32 s15, s95, s15
	s_or_b32 s16, s12, 0x1000000
	s_or_b32 s95, s13, 0x1000000
	v_cmp_le_u32_e64 s[8:9], s16, v8
	v_cmp_le_u32_e64 s[2:3], s95, v6
	s_bcnt1_i32_b64 s62, s[8:9]
	s_bcnt1_i32_b64 s97, s[2:3]
	s_cmp_gt_u32 s62, 15
	s_cselect_b32 s12, s16, s12
	s_cmp_gt_u32 s97, 15
	s_cselect_b32 s13, s95, s13
	s_or_b32 s16, s14, 0x1000000
	s_or_b32 s95, s15, 0x1000000
	v_cmp_le_u32_e64 s[8:9], s16, v4
	v_cmp_le_u32_e64 s[2:3], s95, v2
	s_bcnt1_i32_b64 s62, s[8:9]
	s_bcnt1_i32_b64 s97, s[2:3]
	s_cmp_gt_u32 s62, 15
	s_cselect_b32 s14, s16, s14
	s_cmp_gt_u32 s97, 15
	s_cselect_b32 s15, s95, s15
	s_or_b32 s16, s12, 0x800000
	s_or_b32 s95, s13, 0x800000
	v_cmp_le_u32_e64 s[8:9], s16, v8
	v_cmp_le_u32_e64 s[2:3], s95, v6
	s_bcnt1_i32_b64 s62, s[8:9]
	s_bcnt1_i32_b64 s97, s[2:3]
	s_cmp_gt_u32 s62, 15
	s_cselect_b32 s12, s16, s12
	s_cmp_gt_u32 s97, 15
	s_cselect_b32 s13, s95, s13
	s_or_b32 s16, s14, 0x800000
	s_or_b32 s95, s15, 0x800000
	v_cmp_le_u32_e64 s[8:9], s16, v4
	v_cmp_le_u32_e64 s[2:3], s95, v2
	s_bcnt1_i32_b64 s62, s[8:9]
	s_bcnt1_i32_b64 s97, s[2:3]
	s_cmp_gt_u32 s62, 15
	s_cselect_b32 s14, s16, s14
	s_cmp_gt_u32 s97, 15
	s_cselect_b32 s15, s95, s15
	s_or_b32 s16, s12, 0x400000
	s_or_b32 s95, s13, 0x400000
	v_cmp_le_u32_e64 s[8:9], s16, v8
	v_cmp_le_u32_e64 s[2:3], s95, v6
	s_bcnt1_i32_b64 s62, s[8:9]
	s_bcnt1_i32_b64 s97, s[2:3]
	s_cmp_gt_u32 s62, 15
	s_cselect_b32 s12, s16, s12
	s_cmp_gt_u32 s97, 15
	s_cselect_b32 s13, s95, s13
	s_or_b32 s16, s14, 0x400000
	s_or_b32 s95, s15, 0x400000
	v_cmp_le_u32_e64 s[8:9], s16, v4
	v_cmp_le_u32_e64 s[2:3], s95, v2
	s_bcnt1_i32_b64 s62, s[8:9]
	s_bcnt1_i32_b64 s97, s[2:3]
	s_cmp_gt_u32 s62, 15
	s_cselect_b32 s14, s16, s14
	s_cmp_gt_u32 s97, 15
	s_cselect_b32 s15, s95, s15
	s_or_b32 s16, s12, 0x200000
	s_or_b32 s95, s13, 0x200000
	v_cmp_le_u32_e64 s[8:9], s16, v8
	v_cmp_le_u32_e64 s[2:3], s95, v6
	s_bcnt1_i32_b64 s62, s[8:9]
	s_bcnt1_i32_b64 s97, s[2:3]
	s_cmp_gt_u32 s62, 15
	s_cselect_b32 s12, s16, s12
	s_cmp_gt_u32 s97, 15
	s_cselect_b32 s13, s95, s13
	s_or_b32 s16, s14, 0x200000
	s_or_b32 s95, s15, 0x200000
	v_cmp_le_u32_e64 s[8:9], s16, v4
	v_cmp_le_u32_e64 s[2:3], s95, v2
	s_bcnt1_i32_b64 s62, s[8:9]
	s_bcnt1_i32_b64 s97, s[2:3]
	s_cmp_gt_u32 s62, 15
	s_cselect_b32 s14, s16, s14
	s_cmp_gt_u32 s97, 15
	s_cselect_b32 s15, s95, s15
	s_or_b32 s16, s12, 0x100000
	s_or_b32 s95, s13, 0x100000
	v_cmp_le_u32_e64 s[8:9], s16, v8
	v_cmp_le_u32_e64 s[2:3], s95, v6
	s_bcnt1_i32_b64 s62, s[8:9]
	s_bcnt1_i32_b64 s97, s[2:3]
	s_cmp_gt_u32 s62, 15
	s_cselect_b32 s12, s16, s12
	s_cmp_gt_u32 s97, 15
	s_cselect_b32 s13, s95, s13
	s_or_b32 s16, s14, 0x100000
	s_or_b32 s95, s15, 0x100000
	v_cmp_le_u32_e64 s[8:9], s16, v4
	v_cmp_le_u32_e64 s[2:3], s95, v2
	s_bcnt1_i32_b64 s62, s[8:9]
	s_bcnt1_i32_b64 s97, s[2:3]
	s_cmp_gt_u32 s62, 15
	s_cselect_b32 s14, s16, s14
	s_cmp_gt_u32 s97, 15
	s_cselect_b32 s15, s95, s15
	s_or_b32 s16, s12, 0x80000
	s_or_b32 s95, s13, 0x80000
	v_cmp_le_u32_e64 s[8:9], s16, v8
	v_cmp_le_u32_e64 s[2:3], s95, v6
	s_bcnt1_i32_b64 s62, s[8:9]
	s_bcnt1_i32_b64 s97, s[2:3]
	s_cmp_gt_u32 s62, 15
	s_cselect_b32 s12, s16, s12
	s_cmp_gt_u32 s97, 15
	s_cselect_b32 s13, s95, s13
	s_or_b32 s16, s14, 0x80000
	s_or_b32 s95, s15, 0x80000
	v_cmp_le_u32_e64 s[8:9], s16, v4
	v_cmp_le_u32_e64 s[2:3], s95, v2
	s_bcnt1_i32_b64 s62, s[8:9]
	s_bcnt1_i32_b64 s97, s[2:3]
	s_cmp_gt_u32 s62, 15
	s_cselect_b32 s14, s16, s14
	s_cmp_gt_u32 s97, 15
	s_cselect_b32 s15, s95, s15
	s_or_b32 s16, s12, 0x40000
	s_or_b32 s95, s13, 0x40000
	v_cmp_le_u32_e64 s[8:9], s16, v8
	v_cmp_le_u32_e64 s[2:3], s95, v6
	s_bcnt1_i32_b64 s62, s[8:9]
	s_bcnt1_i32_b64 s97, s[2:3]
	s_cmp_gt_u32 s62, 15
	s_cselect_b32 s12, s16, s12
	s_cmp_gt_u32 s97, 15
	s_cselect_b32 s13, s95, s13
	s_or_b32 s16, s14, 0x40000
	s_or_b32 s95, s15, 0x40000
	v_cmp_le_u32_e64 s[8:9], s16, v4
	v_cmp_le_u32_e64 s[2:3], s95, v2
	s_bcnt1_i32_b64 s62, s[8:9]
	s_bcnt1_i32_b64 s97, s[2:3]
	s_cmp_gt_u32 s62, 15
	s_cselect_b32 s14, s16, s14
	s_cmp_gt_u32 s97, 15
	s_cselect_b32 s15, s95, s15
	s_or_b32 s16, s12, 0x20000
	s_or_b32 s95, s13, 0x20000
	v_cmp_le_u32_e64 s[8:9], s16, v8
	v_cmp_le_u32_e64 s[2:3], s95, v6
	s_bcnt1_i32_b64 s62, s[8:9]
	s_bcnt1_i32_b64 s97, s[2:3]
	s_cmp_gt_u32 s62, 15
	s_cselect_b32 s12, s16, s12
	s_cmp_gt_u32 s97, 15
	s_cselect_b32 s13, s95, s13
	s_or_b32 s16, s14, 0x20000
	s_or_b32 s95, s15, 0x20000
	v_cmp_le_u32_e64 s[8:9], s16, v4
	v_cmp_le_u32_e64 s[2:3], s95, v2
	s_bcnt1_i32_b64 s62, s[8:9]
	s_bcnt1_i32_b64 s97, s[2:3]
	s_cmp_gt_u32 s62, 15
	s_cselect_b32 s14, s16, s14
	s_cmp_gt_u32 s97, 15
	s_cselect_b32 s15, s95, s15
	s_or_b32 s16, s12, 0x10000
	s_or_b32 s95, s13, 0x10000
	v_cmp_le_u32_e64 s[8:9], s16, v8
	v_cmp_le_u32_e64 s[2:3], s95, v6
	s_bcnt1_i32_b64 s62, s[8:9]
	s_bcnt1_i32_b64 s97, s[2:3]
	s_cmp_gt_u32 s62, 15
	s_cselect_b32 s12, s16, s12
	s_cmp_gt_u32 s97, 15
	s_cselect_b32 s13, s95, s13
	s_or_b32 s16, s14, 0x10000
	s_or_b32 s95, s15, 0x10000
	v_cmp_le_u32_e64 s[8:9], s16, v4
	v_cmp_le_u32_e64 s[2:3], s95, v2
	s_bcnt1_i32_b64 s62, s[8:9]
	s_bcnt1_i32_b64 s97, s[2:3]
	s_cmp_gt_u32 s62, 15
	s_cselect_b32 s14, s16, s14
	s_cmp_gt_u32 s97, 15
	s_cselect_b32 s15, s95, s15
	s_or_b32 s16, s12, 0x8000
	s_or_b32 s95, s13, 0x8000
	v_cmp_le_u32_e64 s[8:9], s16, v8
	v_cmp_le_u32_e64 s[2:3], s95, v6
	s_bcnt1_i32_b64 s62, s[8:9]
	s_bcnt1_i32_b64 s97, s[2:3]
	s_cmp_gt_u32 s62, 15
	s_cselect_b32 s12, s16, s12
	s_cmp_gt_u32 s97, 15
	s_cselect_b32 s13, s95, s13
	s_or_b32 s16, s14, 0x8000
	s_or_b32 s95, s15, 0x8000
	v_cmp_le_u32_e64 s[8:9], s16, v4
	v_cmp_le_u32_e64 s[2:3], s95, v2
	s_bcnt1_i32_b64 s62, s[8:9]
	s_bcnt1_i32_b64 s97, s[2:3]
	s_cmp_gt_u32 s62, 15
	s_cselect_b32 s14, s16, s14
	s_cmp_gt_u32 s97, 15
	s_cselect_b32 s15, s95, s15
	s_or_b32 s16, s12, 0x4000
	s_or_b32 s95, s13, 0x4000
	v_cmp_le_u32_e64 s[8:9], s16, v8
	v_cmp_le_u32_e64 s[2:3], s95, v6
	s_bcnt1_i32_b64 s62, s[8:9]
	s_bcnt1_i32_b64 s97, s[2:3]
	s_cmp_gt_u32 s62, 15
	s_cselect_b32 s12, s16, s12
	s_cmp_gt_u32 s97, 15
	s_cselect_b32 s13, s95, s13
	s_or_b32 s16, s14, 0x4000
	s_or_b32 s95, s15, 0x4000
	v_cmp_le_u32_e64 s[8:9], s16, v4
	v_cmp_le_u32_e64 s[2:3], s95, v2
	s_bcnt1_i32_b64 s62, s[8:9]
	s_bcnt1_i32_b64 s97, s[2:3]
	s_cmp_gt_u32 s62, 15
	s_cselect_b32 s14, s16, s14
	s_cmp_gt_u32 s97, 15
	s_cselect_b32 s15, s95, s15
	s_or_b32 s16, s12, 0x2000
	s_or_b32 s95, s13, 0x2000
	v_cmp_le_u32_e64 s[8:9], s16, v8
	v_cmp_le_u32_e64 s[2:3], s95, v6
	s_bcnt1_i32_b64 s62, s[8:9]
	s_bcnt1_i32_b64 s97, s[2:3]
	s_cmp_gt_u32 s62, 15
	s_cselect_b32 s12, s16, s12
	s_cmp_gt_u32 s97, 15
	s_cselect_b32 s13, s95, s13
	s_or_b32 s16, s14, 0x2000
	s_or_b32 s95, s15, 0x2000
	v_cmp_le_u32_e64 s[8:9], s16, v4
	v_cmp_le_u32_e64 s[2:3], s95, v2
	s_bcnt1_i32_b64 s62, s[8:9]
	s_bcnt1_i32_b64 s97, s[2:3]
	s_cmp_gt_u32 s62, 15
	s_cselect_b32 s14, s16, s14
	s_cmp_gt_u32 s97, 15
	s_cselect_b32 s15, s95, s15
	s_or_b32 s16, s12, 0x1000
	s_or_b32 s95, s13, 0x1000
	v_cmp_le_u32_e64 s[8:9], s16, v8
	v_cmp_le_u32_e64 s[2:3], s95, v6
	s_bcnt1_i32_b64 s62, s[8:9]
	s_bcnt1_i32_b64 s97, s[2:3]
	s_cmp_gt_u32 s62, 15
	s_cselect_b32 s12, s16, s12
	s_cmp_gt_u32 s97, 15
	s_cselect_b32 s13, s95, s13
	s_or_b32 s16, s14, 0x1000
	s_or_b32 s95, s15, 0x1000
	v_cmp_le_u32_e64 s[8:9], s16, v4
	v_cmp_le_u32_e64 s[2:3], s95, v2
	s_bcnt1_i32_b64 s62, s[8:9]
	s_bcnt1_i32_b64 s97, s[2:3]
	s_cmp_gt_u32 s62, 15
	s_cselect_b32 s14, s16, s14
	s_cmp_gt_u32 s97, 15
	s_cselect_b32 s15, s95, s15
	s_or_b32 s16, s12, 0x800
	s_or_b32 s95, s13, 0x800
	v_cmp_le_u32_e64 s[8:9], s16, v8
	v_cmp_le_u32_e64 s[2:3], s95, v6
	s_bcnt1_i32_b64 s62, s[8:9]
	s_bcnt1_i32_b64 s97, s[2:3]
	s_cmp_gt_u32 s62, 15
	s_cselect_b32 s12, s16, s12
	s_cmp_gt_u32 s97, 15
	s_cselect_b32 s13, s95, s13
	s_or_b32 s16, s14, 0x800
	s_or_b32 s95, s15, 0x800
	v_cmp_le_u32_e64 s[8:9], s16, v4
	v_cmp_le_u32_e64 s[2:3], s95, v2
	s_bcnt1_i32_b64 s62, s[8:9]
	s_bcnt1_i32_b64 s97, s[2:3]
	s_cmp_gt_u32 s62, 15
	s_cselect_b32 s14, s16, s14
	s_cmp_gt_u32 s97, 15
	s_cselect_b32 s15, s95, s15
	s_or_b32 s16, s12, 0x400
	s_or_b32 s95, s13, 0x400
	v_cmp_le_u32_e64 s[8:9], s16, v8
	v_cmp_le_u32_e64 s[2:3], s95, v6
	s_bcnt1_i32_b64 s62, s[8:9]
	s_bcnt1_i32_b64 s97, s[2:3]
	s_cmp_gt_u32 s62, 15
	s_cselect_b32 s12, s16, s12
	s_cmp_gt_u32 s97, 15
	s_cselect_b32 s13, s95, s13
	s_or_b32 s16, s14, 0x400
	s_or_b32 s95, s15, 0x400
	v_cmp_le_u32_e64 s[8:9], s16, v4
	v_cmp_le_u32_e64 s[2:3], s95, v2
	s_bcnt1_i32_b64 s62, s[8:9]
	s_bcnt1_i32_b64 s97, s[2:3]
	s_cmp_gt_u32 s62, 15
	s_cselect_b32 s14, s16, s14
	s_cmp_gt_u32 s97, 15
	s_cselect_b32 s15, s95, s15
	s_or_b32 s16, s12, 0x200
	s_or_b32 s95, s13, 0x200
	v_cmp_le_u32_e64 s[8:9], s16, v8
	v_cmp_le_u32_e64 s[2:3], s95, v6
	s_bcnt1_i32_b64 s62, s[8:9]
	s_bcnt1_i32_b64 s97, s[2:3]
	s_cmp_gt_u32 s62, 15
	s_cselect_b32 s12, s16, s12
	s_cmp_gt_u32 s97, 15
	s_cselect_b32 s13, s95, s13
	s_or_b32 s16, s14, 0x200
	s_or_b32 s95, s15, 0x200
	v_cmp_le_u32_e64 s[8:9], s16, v4
	v_cmp_le_u32_e64 s[2:3], s95, v2
	s_bcnt1_i32_b64 s62, s[8:9]
	s_bcnt1_i32_b64 s97, s[2:3]
	s_cmp_gt_u32 s62, 15
	s_cselect_b32 s14, s16, s14
	s_cmp_gt_u32 s97, 15
	s_cselect_b32 s15, s95, s15
	s_or_b32 s16, s12, 0x100
	s_or_b32 s95, s13, 0x100
	v_cmp_le_u32_e64 s[8:9], s16, v8
	v_cmp_le_u32_e64 s[2:3], s95, v6
	s_bcnt1_i32_b64 s62, s[8:9]
	s_bcnt1_i32_b64 s97, s[2:3]
	s_cmp_gt_u32 s62, 15
	s_cselect_b32 s12, s16, s12
	s_cmp_gt_u32 s97, 15
	s_cselect_b32 s13, s95, s13
	s_or_b32 s16, s14, 0x100
	s_or_b32 s95, s15, 0x100
	v_cmp_le_u32_e64 s[8:9], s16, v4
	v_cmp_le_u32_e64 s[2:3], s95, v2
	s_bcnt1_i32_b64 s62, s[8:9]
	s_bcnt1_i32_b64 s97, s[2:3]
	s_cmp_gt_u32 s62, 15
	s_cselect_b32 s14, s16, s14
	s_cmp_gt_u32 s97, 15
	s_cselect_b32 s15, s95, s15
	s_or_b32 s16, s12, 0x80
	s_or_b32 s95, s13, 0x80
	v_cmp_le_u32_e64 s[8:9], s16, v8
	v_cmp_le_u32_e64 s[2:3], s95, v6
	s_bcnt1_i32_b64 s62, s[8:9]
	s_bcnt1_i32_b64 s97, s[2:3]
	s_cmp_gt_u32 s62, 15
	s_cselect_b32 s12, s16, s12
	s_cmp_gt_u32 s97, 15
	s_cselect_b32 s13, s95, s13
	s_or_b32 s16, s14, 0x80
	s_or_b32 s95, s15, 0x80
	v_cmp_le_u32_e64 s[8:9], s16, v4
	v_cmp_le_u32_e64 s[2:3], s95, v2
	s_bcnt1_i32_b64 s62, s[8:9]
	s_bcnt1_i32_b64 s97, s[2:3]
	s_cmp_gt_u32 s62, 15
	s_cselect_b32 s14, s16, s14
	s_cmp_gt_u32 s97, 15
	s_cselect_b32 s15, s95, s15
	s_or_b32 s16, s12, 0x40
	s_or_b32 s95, s13, 0x40
	v_cmp_le_u32_e64 s[8:9], s16, v8
	v_cmp_le_u32_e64 s[2:3], s95, v6
	s_bcnt1_i32_b64 s62, s[8:9]
	s_bcnt1_i32_b64 s97, s[2:3]
	s_cmp_gt_u32 s62, 15
	s_cselect_b32 s12, s16, s12
	s_cmp_gt_u32 s97, 15
	s_cselect_b32 s13, s95, s13
	s_or_b32 s16, s14, 0x40
	s_or_b32 s95, s15, 0x40
	v_cmp_le_u32_e64 s[8:9], s16, v4
	v_cmp_le_u32_e64 s[2:3], s95, v2
	s_bcnt1_i32_b64 s62, s[8:9]
	s_bcnt1_i32_b64 s97, s[2:3]
	s_cmp_gt_u32 s62, 15
	s_cselect_b32 s14, s16, s14
	s_cmp_gt_u32 s97, 15
	s_cselect_b32 s15, s95, s15
	s_or_b32 s16, s12, 32
	s_or_b32 s95, s13, 32
	v_cmp_le_u32_e64 s[8:9], s16, v8
	v_cmp_le_u32_e64 s[2:3], s95, v6
	s_bcnt1_i32_b64 s62, s[8:9]
	s_bcnt1_i32_b64 s97, s[2:3]
	s_cmp_gt_u32 s62, 15
	s_cselect_b32 s12, s16, s12
	s_cmp_gt_u32 s97, 15
	s_cselect_b32 s13, s95, s13
	s_or_b32 s16, s14, 32
	s_or_b32 s95, s15, 32
	v_cmp_le_u32_e64 s[8:9], s16, v4
	v_cmp_le_u32_e64 s[2:3], s95, v2
	s_bcnt1_i32_b64 s62, s[8:9]
	s_bcnt1_i32_b64 s97, s[2:3]
	s_cmp_gt_u32 s62, 15
	s_cselect_b32 s14, s16, s14
	s_cmp_gt_u32 s97, 15
	s_cselect_b32 s15, s95, s15
	s_or_b32 s16, s12, 16
	s_or_b32 s95, s13, 16
	v_cmp_le_u32_e64 s[8:9], s16, v8
	v_cmp_le_u32_e64 s[2:3], s95, v6
	s_bcnt1_i32_b64 s62, s[8:9]
	s_bcnt1_i32_b64 s97, s[2:3]
	s_cmp_gt_u32 s62, 15
	s_cselect_b32 s12, s16, s12
	s_cmp_gt_u32 s97, 15
	s_cselect_b32 s13, s95, s13
	s_or_b32 s16, s14, 16
	s_or_b32 s95, s15, 16
	v_cmp_le_u32_e64 s[8:9], s16, v4
	v_cmp_le_u32_e64 s[2:3], s95, v2
	s_bcnt1_i32_b64 s62, s[8:9]
	s_bcnt1_i32_b64 s97, s[2:3]
	s_cmp_gt_u32 s62, 15
	s_cselect_b32 s14, s16, s14
	s_cmp_gt_u32 s97, 15
	s_cselect_b32 s15, s95, s15
	s_or_b32 s16, s12, 8
	s_or_b32 s95, s13, 8
	v_cmp_le_u32_e64 s[8:9], s16, v8
	v_cmp_le_u32_e64 s[2:3], s95, v6
	s_bcnt1_i32_b64 s62, s[8:9]
	s_bcnt1_i32_b64 s97, s[2:3]
	s_cmp_gt_u32 s62, 15
	s_cselect_b32 s12, s16, s12
	s_cmp_gt_u32 s97, 15
	s_cselect_b32 s13, s95, s13
	s_or_b32 s16, s14, 8
	s_or_b32 s95, s15, 8
	v_cmp_le_u32_e64 s[8:9], s16, v4
	v_cmp_le_u32_e64 s[2:3], s95, v2
	s_bcnt1_i32_b64 s62, s[8:9]
	s_bcnt1_i32_b64 s97, s[2:3]
	s_cmp_gt_u32 s62, 15
	s_cselect_b32 s14, s16, s14
	s_cmp_gt_u32 s97, 15
	s_cselect_b32 s15, s95, s15
	s_or_b32 s16, s12, 4
	s_or_b32 s95, s13, 4
	v_cmp_le_u32_e64 s[8:9], s16, v8
	v_cmp_le_u32_e64 s[2:3], s95, v6
	s_bcnt1_i32_b64 s62, s[8:9]
	s_bcnt1_i32_b64 s97, s[2:3]
	s_cmp_gt_u32 s62, 15
	s_cselect_b32 s12, s16, s12
	s_cmp_gt_u32 s97, 15
	s_cselect_b32 s13, s95, s13
	s_or_b32 s16, s14, 4
	s_or_b32 s95, s15, 4
	v_cmp_le_u32_e64 s[8:9], s16, v4
	v_cmp_le_u32_e64 s[2:3], s95, v2
	s_bcnt1_i32_b64 s62, s[8:9]
	s_bcnt1_i32_b64 s97, s[2:3]
	s_cmp_gt_u32 s62, 15
	s_cselect_b32 s14, s16, s14
	s_cmp_gt_u32 s97, 15
	s_cselect_b32 s15, s95, s15
	s_or_b32 s16, s12, 2
	v_cmp_le_u32_e64 s[8:9], s16, v8
	s_bcnt1_i32_b64 s62, s[8:9]
	v_cmp_gt_u64_e64 s[2:3], s[62:63], 15
	s_and_b64 s[2:3], s[2:3], exec
	s_cselect_b32 s12, s16, s12
	s_or_b32 s16, s13, 2
	v_cmp_le_u32_e64 s[8:9], s16, v6
	s_bcnt1_i32_b64 s62, s[8:9]
	v_cmp_gt_u64_e64 s[2:3], s[62:63], 15
	s_and_b64 s[2:3], s[2:3], exec
	s_cselect_b32 s29, s16, s13
	s_or_b32 s13, s14, 2
	v_cmp_le_u32_e64 s[8:9], s13, v4
	s_bcnt1_i32_b64 s62, s[8:9]
	v_cmp_gt_u64_e64 s[2:3], s[62:63], 15
	s_and_b64 s[2:3], s[2:3], exec
	s_cselect_b32 s27, s13, s14
	s_or_b32 s13, s15, 2
	v_cmp_le_u32_e64 s[8:9], s13, v2
	s_bcnt1_i32_b64 s62, s[8:9]
	v_cmp_gt_u64_e64 s[2:3], s[62:63], 15
	s_and_b64 s[2:3], s[2:3], exec
	s_cselect_b32 s3, s13, s15
	s_or_b32 s2, s12, 1
	v_cmp_le_u32_e64 s[8:9], s2, v8
	s_bcnt1_i32_b64 s62, s[8:9]
	v_cmp_gt_u64_e64 s[8:9], s[62:63], 15
	s_and_b64 s[8:9], s[8:9], exec
	s_cselect_b32 s20, s2, s12
	v_cmp_lt_u32_e64 s[16:17], s20, v8
	v_cmp_eq_u32_e64 s[20:21], s20, v8
	s_bcnt1_i32_b64 s22, s[16:17]
	s_sub_i32 s22, 16, s22
	v_and_b32_e32 v9, s20, v186
	v_and_b32_e32 v8, s21, v167
	v_bcnt_u32_b32 v9, v9, 0
	v_bcnt_u32_b32 v8, v8, v9
	v_cmp_gt_i32_e64 s[22:23], s22, v8
	s_and_b64 s[20:21], s[20:21], s[22:23]
	s_or_b64 s[20:21], s[16:17], s[20:21]
	v_cmp_lt_f32_e64 s[16:17], s88, v7
	s_and_b64 s[16:17], s[20:21], s[16:17]
	s_or_b32 s30, s29, 1
	s_or_b32 s28, s27, 1
	s_or_b32 s26, s3, 1
	v_cndmask_b32_e64 v7, 0, 1, s[16:17]
	v_cmp_le_u32_e64 s[14:15], s30, v6
	v_cmp_le_u32_e64 s[12:13], s28, v4
	v_cmp_le_u32_e64 s[8:9], s26, v2
	s_add_i32 s2, s25, 0
	v_cmp_ne_u32_e64 s[20:21], 0, v7
	s_and_saveexec_b64 s[16:17], s[6:7]
	s_add_i32 s22, s2, 0x10800
	v_mov_b32_e32 v7, s22
	v_mov_b64_e32 v[8:9], s[20:21]
	ds_write_b64 v7, v[8:9]
	s_or_b64 exec, exec, s[16:17]
	s_bcnt1_i32_b64 s62, s[14:15]
	v_cmp_gt_u64_e64 s[14:15], s[62:63], 15
	s_and_b64 s[14:15], s[14:15], exec
	s_cselect_b32 s16, s30, s29
	v_cmp_lt_u32_e64 s[14:15], s16, v6
	v_cmp_eq_u32_e64 s[16:17], s16, v6
	s_bcnt1_i32_b64 s20, s[14:15]
	s_sub_i32 s20, 16, s20
	v_and_b32_e32 v7, s16, v186
	v_and_b32_e32 v6, s17, v167
	v_bcnt_u32_b32 v7, v7, 0
	v_bcnt_u32_b32 v6, v6, v7
	v_cmp_gt_i32_e64 s[20:21], s20, v6
	s_and_b64 s[16:17], s[16:17], s[20:21]
	s_or_b64 s[16:17], s[14:15], s[16:17]
	v_cmp_lt_f32_e64 s[14:15], s88, v5
	s_and_b64 s[14:15], s[16:17], s[14:15]
	s_nop 0
	v_cndmask_b32_e64 v5, 0, 1, s[14:15]
	v_cmp_ne_u32_e64 s[16:17], 0, v5
	s_and_saveexec_b64 s[14:15], s[6:7]
	s_add_i32 s20, s2, 0x10808
	v_mov_b32_e32 v5, s20
	v_mov_b64_e32 v[6:7], s[16:17]
	ds_write_b64 v5, v[6:7]
	s_or_b64 exec, exec, s[14:15]
	s_bcnt1_i32_b64 s62, s[12:13]
	v_cmp_gt_u64_e64 s[12:13], s[62:63], 15
	s_and_b64 s[12:13], s[12:13], exec
	s_cselect_b32 s14, s28, s27
	v_cmp_lt_u32_e64 s[12:13], s14, v4
	v_cmp_eq_u32_e64 s[14:15], s14, v4
	s_bcnt1_i32_b64 s16, s[12:13]
	s_sub_i32 s16, 16, s16
	v_and_b32_e32 v5, s14, v186
	v_and_b32_e32 v4, s15, v167
	v_bcnt_u32_b32 v5, v5, 0
	v_bcnt_u32_b32 v4, v4, v5
	v_cmp_gt_i32_e64 s[16:17], s16, v4
	s_and_b64 s[14:15], s[14:15], s[16:17]
	s_or_b64 s[14:15], s[12:13], s[14:15]
	v_cmp_lt_f32_e64 s[12:13], s88, v3
	s_and_b64 s[12:13], s[14:15], s[12:13]
	s_nop 0
	v_cndmask_b32_e64 v3, 0, 1, s[12:13]
	v_cmp_ne_u32_e64 s[14:15], 0, v3
	s_and_saveexec_b64 s[12:13], s[6:7]
	s_add_i32 s16, s2, 0x10810
	v_mov_b32_e32 v3, s16
	v_mov_b64_e32 v[4:5], s[14:15]
	ds_write_b64 v3, v[4:5]
	s_or_b64 exec, exec, s[12:13]
	s_bcnt1_i32_b64 s62, s[8:9]
	v_cmp_gt_u64_e64 s[8:9], s[62:63], 15
	s_and_b64 s[8:9], s[8:9], exec
	s_cselect_b32 s3, s26, s3
	v_cmp_eq_u32_e64 s[12:13], s3, v2
	v_cmp_lt_u32_e64 s[8:9], s3, v2
	s_bcnt1_i32_b64 s3, s[8:9]
	v_and_b32_e32 v3, s12, v186
	v_and_b32_e32 v2, s13, v167
	v_bcnt_u32_b32 v3, v3, 0
	s_sub_i32 s3, 16, s3
	v_bcnt_u32_b32 v2, v2, v3
	v_cmp_gt_i32_e64 s[14:15], s3, v2
	s_and_b64 s[12:13], s[12:13], s[14:15]
	s_or_b64 s[12:13], s[8:9], s[12:13]
	v_cmp_lt_f32_e64 s[8:9], s88, v1
	s_and_b64 s[8:9], s[12:13], s[8:9]
	s_nop 0
	v_cndmask_b32_e64 v1, 0, 1, s[8:9]
	v_cmp_ne_u32_e64 s[12:13], 0, v1
	s_and_saveexec_b64 s[8:9], s[6:7]
	s_cbranch_execz .LBB0_798
	s_add_i32 s2, s2, 0x10818
	v_mov_b32_e32 v1, s2
	v_mov_b64_e32 v[2:3], s[12:13]
	ds_write_b64 v1, v[2:3]
	s_branch .LBB0_798
